# G2 consumes newest tiles first; window pass reuses the bias table built by the selected-block pass
# speedup vs baseline: 1.0218x; 1.0029x over previous
; template <int MODE>
; __device__ __forceinline__ void attn_pass(LAS unsigned char* lds, const bf16_t* base, int gk, int q0, const float* relb_b, const unsigned* selrow, f32x4 (&o)[2][4]) {
;     ...
;     bf16x8 qf[2][2];
; #pragma unroll
;     for (int qt = 0; qt < 2; ++qt)
; #pragma unroll
;         for (int ks = 0; ks < 2; ++ks) qf[qt][ks] = *(const bf16x8*)(qp + (size_t)(qw0 + qt * 16 + c) * QP + ks * 32 + g * 8);
;     const int kb_hi = q0 >> 6;
;     unsigned todo;
;     unsigned sel[2] = {0xffffffffu, 0xffffffffu};
;     unsigned selw = 0xffffffffu;
;     if (MODE == MODE_BSLC) {
;         sel[0] = selrow[qw0 + c]; sel[1] = selrow[qw0 + 16 + c];
;         unsigned u = sel[0] | sel[1];
; #pragma unroll
;         for (int off = 1; off < 64; off <<= 1) u |= __shfl_xor(u, off);
;         selw = __builtin_amdgcn_readfirstlane(u);
;         unsigned v = selrow[q0 + lane];
; #pragma unroll
;         for (int off = 1; off < 64; off <<= 1) v |= __shfl_xor(v, off);
;         todo = __builtin_amdgcn_readfirstlane(v) & (0xffffffffu >> (31 - kb_hi));
;     } else {
;         const int kb_lo = kb_hi >= 8 ? kb_hi - 8 : 0;
;         todo = (0xffffffffu >> (31 - kb_hi)) & (0xffffffffu << kb_lo);
;     }
;     __syncthreads();
;     if (tid < 512) { const int e = tid; lutw[e] = relb_b[(int)T5B[e & 127] * 16 + gk * 4 + (e >> 7)] * LOG2E; }
;     const float bias_far = relb_b[31 * 16 + h] * LOG2E;
;     ...
;     for (int qt = 0; qt < 2; ++qt) { float l = lrun[qt]; l += __shfl_xor(l, 16); l += __shfl_xor(l, 32);
.LBB0_143:
	v_mov_b32_e32 v41, v214
	v_mov_b32_e32 v3, v0
	v_readfirstlane_b32 s6, v41
	s_bfe_u32 s7, s6, 0x20006
	s_or_b32 s8, s7, s40
	s_lshl_b32 s0, s8, 7
	s_add_u32 s0, s13, s0
	s_addc_u32 s1, s41, 0
	s_ashr_i32 s6, s6, 3
	s_andn2_b32 s6, s6, 31
	v_and_b32_e32 v40, 15, v41
	v_bfe_u32 v42, v41, 4, 2
	s_add_i32 s6, s6, s36
	v_or_b32_e32 v185, s6, v40
	v_lshlrev_b32_e32 v2, 4, v42
	v_lshl_add_u64 v[44:45], s[0:1], 0, v[2:3]
	v_or_b32_e32 v3, 16, v185
	v_mad_i64_i32 v[46:47], s[0:1], v185, s85, v[44:45]
	v_mad_i64_i32 v[44:45], s[0:1], v3, s85, v[44:45]
	global_load_dwordx4 v[72:75], v[46:47], off offset:1536
	global_load_dwordx4 v[76:79], v[46:47], off offset:1600
	global_load_dwordx4 v[80:83], v[44:45], off offset:1536
	global_load_dwordx4 v[84:87], v[44:45], off offset:1600
	ds_bpermute_b32 v3, v178, v154
	ds_bpermute_b32 v43, v178, v1
	v_cmp_gt_i32_e32 vcc, s33, v41
	s_waitcnt lgkmcnt(0)
	s_barrier
	v_add_f32_e32 v181, v154, v3
	v_add_f32_e32 v183, v1, v43
	ds_bpermute_b32 v182, v179, v181
	ds_bpermute_b32 v184, v179, v183
	s_waitcnt lgkmcnt(0)
	s_mov_b64 s[0:1], exec
	s_branch .LBB0_145
	v_and_b32_e32 v1, 0x7f, v41
	s_getpc_b64 s[10:11]
	s_add_u32 s10, s10, T5B@rel32@lo+4
	s_addc_u32 s11, s11, T5B@rel32@hi+12
	global_load_ubyte v1, v1, s[10:11]
	v_ashrrev_i32_e32 v3, 7, v41
	v_readlane_b32 s44, v255, 4
	v_readlane_b32 s48, v255, 8
	v_readlane_b32 s49, v255, 9
	v_readlane_b32 s45, v255, 5
	v_readlane_b32 s46, v255, 6
	v_readlane_b32 s47, v255, 7
	v_readlane_b32 s50, v255, 10
	v_readlane_b32 s51, v255, 11
	v_readlane_b32 s52, v255, 12
	v_readlane_b32 s53, v255, 13
	v_readlane_b32 s54, v255, 14
	v_readlane_b32 s55, v255, 15
	v_readlane_b32 s56, v255, 16
	v_readlane_b32 s57, v255, 17
	v_readlane_b32 s58, v255, 18
	v_readlane_b32 s59, v255, 19
	s_waitcnt vmcnt(0)
	v_lshlrev_b32_e32 v1, 4, v1
	v_add3_u32 v44, v3, s40, v1
	v_ashrrev_i32_e32 v45, 31, v44
	v_lshl_add_u64 v[44:45], v[44:45], 2, s[48:49]
	global_load_dword v1, v[44:45], off offset:32
	v_lshl_add_u32 v3, v41, 2, 0
	s_waitcnt vmcnt(0)
	v_mul_f32_e32 v1, 0x3fb8aa3b, v1
	ds_write_b32 v3, v1 offset:36864

; #define LAS __attribute__((address_space(3)))
;     __device__ __forceinline__ bool tile(long L, int& pm, int& pn) const {
;         if (L >= nwg) return false;
;         int wgid = (int)L; { const int q = nwg / NXCD, r = nwg % NXCD, xcd = wgid % NXCD, off = wgid / NXCD; wgid = (xcd < r ? xcd * (q + 1) : r * (q + 1) + (xcd - r) * q) + off; }
;         const int nig = WGM * nN, gid = wgid / nig, fm = gid * WGM, gsz = (nM - fm) < WGM ? (nM - fm) : WGM;
;         pm = fm + ((wgid % nig) % gsz); pn = (wgid % nig) / gsz; return true;
;     }
;     __device__ __forceinline__ bool next(int i, Unit& u) const {
;         if (!fused) {
;             if (!tile((long)i * G + c, u.pm, u.pn)) return false;
;             u.A = A + (size_t)u.pm * tstep; u.B = B + (size_t)u.pn * tstep; u.nt = nt; u.em = em; u.br = 0; return true;
; __device__ __forceinline__ void utab_build(LAS unsigned char* lds, const StaticOrder& S, int tid) {
;     if (tid < UTAB_MAX) { Unit u; u.A = nullptr; u.B = nullptr; u.nt = 0; u.pm = 0; u.pn = 0; u.em = 0; u.br = 0; const bool ok = S.next(tid, u);
;         LAS unsigned* e = (LAS unsigned*)(lds + UTAB_OFF + tid * 32); const unsigned long long a = (unsigned long long)(uintptr_t)u.A, b = (unsigned long long)(uintptr_t)u.B;
;         e[0] = (unsigned)a; e[1] = (unsigned)(a >> 32); e[2] = (unsigned)b; e[3] = (unsigned)(b >> 32); e[4] = ok ? (unsigned)u.nt : 0u; e[5] = (unsigned)u.pm; e[6] = (unsigned)u.pn; e[7] = (unsigned)(u.em | (u.br << 8)); }
.LBB0_389:
	s_nop 0
	v_readlane_b32 s4, v255, 43
	v_readlane_b32 s5, v255, 44
	s_and_b64 vcc, exec, s[4:5]
	s_cbranch_vccz .LBB0_741
	v_mov_b32_e32 v2, v214
	s_nop 0
	v_cmp_gt_i32_e32 vcc, 64, v2
	s_and_saveexec_b64 s[4:5], vcc
	s_cbranch_execz .LBB0_404
	v_readlane_b32 s6, v255, 37
	v_readlane_b32 s7, v255, 38
	s_lshr_b32 s8, s36, 5
	s_lshl_b32 s11, s10, 9
	s_andn2_b64 vcc, exec, s[6:7]
	s_mov_b64 s[6:7], -1
	s_cbranch_vccnz .LBB0_395
	v_readlane_b32 s6, v254, 14
	v_readlane_b32 s7, v254, 15
	v_mov_b64_e32 v[12:13], 0
	v_mov_b64_e32 v[14:15], 0
	s_waitcnt lgkmcnt(0)
	v_mov_b64_e32 v[8:9], s[6:7]
	v_readlane_b32 s6, v255, 20
	v_readlane_b32 s7, v255, 21
	v_mov_b32_e32 v10, 0
	v_mov_b32_e32 v18, v2
	s_cmp_eq_u32 s14, 3
	s_cbranch_scc0 .Ltab_fwd
	v_sub_u32_e32 v19, 3, v2
	v_cmp_gt_u32_e32 vcc, 4, v2
	s_nop 1
	v_cndmask_b32_e32 v18, v2, v19, vcc
.Ltab_fwd:
	v_mad_i64_i32 v[16:17], s[6:7], v18, s6, v[8:9]
	v_cmp_gt_i64_e32 vcc, s[36:37], v[16:17]
	v_mov_b32_e32 v9, 0
	v_mov_b32_e32 v8, 0
	v_mov_b32_e32 v3, 0
	s_and_saveexec_b64 s[6:7], vcc
	s_cbranch_execz .LBB0_394
	v_cvt_f32_u32_e32 v8, s8
	v_ashrrev_i32_e32 v1, 31, v16
	v_lshrrev_b32_e32 v1, 29, v1
	v_add_u32_e32 v1, v16, v1
	v_rcp_iflag_f32_e32 v8, v8
	v_ashrrev_i32_e32 v3, 3, v1
	v_and_b32_e32 v1, -8, v1
	v_sub_u32_e32 v1, v16, v1
	v_mul_f32_e32 v8, 0x4f7ffffe, v8
	v_cvt_u32_f32_e32 v8, v8
	s_lshr_b32 s9, s36, 3
	v_lshrrev_b32_e32 v9, 31, v1
	v_or_b32_e32 v9, s9, v9
	v_mul_lo_u32 v1, v9, v1
	s_sub_i32 s9, 0, s8
	v_add_u32_e32 v1, v1, v3
	v_mul_lo_u32 v10, s9, v8
	v_sub_u32_e32 v9, 0, v1
	v_mul_hi_u32 v10, v8, v10
	v_max_i32_e32 v9, v1, v9
	v_add_u32_e32 v8, v8, v10
	v_mul_hi_u32 v8, v9, v8
	v_mul_lo_u32 v10, v8, s8
	v_sub_u32_e32 v9, v9, v10
	v_add_u32_e32 v10, 1, v8
	v_cmp_le_u32_e32 vcc, s8, v9
	v_ashrrev_i32_e32 v3, 31, v1
	v_readlane_b32 s16, v255, 48
	v_cndmask_b32_e32 v8, v8, v10, vcc
	v_subrev_u32_e32 v10, s8, v9
	v_cndmask_b32_e32 v9, v9, v10, vcc
	v_add_u32_e32 v10, 1, v8
	v_cmp_le_u32_e32 vcc, s8, v9
	v_readlane_b32 s17, v255, 49
	s_lshr_b32 s9, s10, 6
	v_cndmask_b32_e32 v8, v8, v10, vcc
	v_xor_b32_e32 v8, v8, v3
	v_sub_u32_e32 v3, v8, v3
	v_lshlrev_b32_e32 v8, 3, v3
	v_sub_u32_e32 v9, 0x100, v8
	v_min_i32_e32 v9, 8, v9
	v_sub_u32_e32 v10, 0, v9
	v_max_i32_e32 v10, v9, v10
	v_cvt_f32_u32_e32 v11, v10
	v_mul_lo_u32 v3, v3, s8
	v_sub_u32_e32 v13, 0, v10
	v_sub_u32_e32 v1, v1, v3
	v_rcp_iflag_f32_e32 v11, v11
	v_sub_u32_e32 v12, 0, v1
	v_max_i32_e32 v12, v1, v12
	v_xor_b32_e32 v3, v1, v9
	v_mul_f32_e32 v11, 0x4f7ffffe, v11
	v_cvt_u32_f32_e32 v11, v11
	v_ashrrev_i32_e32 v3, 31, v3
	v_mul_lo_u32 v13, v13, v11
	v_mul_hi_u32 v13, v11, v13
	v_add_u32_e32 v11, v11, v13
	v_mul_hi_u32 v11, v12, v11
	v_mul_lo_u32 v13, v11, v10
	v_sub_u32_e32 v12, v12, v13
	v_add_u32_e32 v13, 1, v11
	v_cmp_ge_u32_e32 vcc, v12, v10
	s_nop 1
	v_cndmask_b32_e32 v11, v11, v13, vcc
	v_sub_u32_e32 v13, v12, v10
	v_cndmask_b32_e32 v12, v12, v13, vcc
	v_add_u32_e32 v13, 1, v11
	v_cmp_ge_u32_e32 vcc, v12, v10
	s_nop 1
	v_cndmask_b32_e32 v10, v11, v13, vcc
	v_xor_b32_e32 v10, v10, v3
	v_sub_u32_e32 v10, v10, v3
	v_mul_lo_u32 v3, v10, v9
	v_mov_b64_e32 v[12:13], s[16:17]
	v_readlane_b32 s16, v255, 50
	v_sub_u32_e32 v1, v1, v3
	v_readlane_b32 s17, v255, 51
	v_add_u32_e32 v9, v1, v8
	v_mov_b32_e32 v8, s9
	v_mov_b64_e32 v[14:15], s[16:17]
	v_readlane_b32 s9, v255, 47
	v_mad_i64_i32 v[12:13], s[26:27], v9, s11, v[12:13]
	v_mad_i64_i32 v[14:15], s[26:27], v10, s11, v[14:15]
	v_mov_b32_e32 v3, s9
